# P3 entry: workgroup barrier + per-wave start skew (7-w)*1.5us so the 8 waves of a workgroup read the same K/V block at the same time (L2 sharing)
# baseline (speedup 1.0000x reference)
; #define LAS __attribute__((address_space(3)))
; __global__ __launch_bounds__(512, 2) void fwd_mega(Args a0_) {
;     ...
;             LAS unsigned char* vl = lds + wave * (32 * VROW);
;             const int nfull = (NPT / ngw) * ngw;
;             for (int task = gw; task < nfull; task += ngw) attn_task<false>(a, vl, lane, task);
;             if (wave == 0) { for (int task = nfull + blockIdx.x; task < NPT; task += G) attn_task<false>(a, vl, lane, task); }
;             if (wave == 4) { for (int task = NPT + ((blockIdx.x + G / 2) % G); task < NTASK; task += G) attn_task<true>(a, vl, lane, task); }
.LBB0_53:
	s_barrier
	v_readlane_b32 s0, v255, 15
	s_sub_i32 s0, 7, s0
	s_cmp_eq_u32 s0, 0
	s_cbranch_scc1 .Lsb_skew_done
.Lsb_skew:
	s_sleep 47
	s_sub_i32 s0, s0, 1
	s_cmp_lg_u32 s0, 0
	s_cbranch_scc1 .Lsb_skew
